# speedup vs baseline: 1.0794x; 1.0002x over previous
.LBB0_1022:
	s_and_b32 s0, s53, 8
	s_and_saveexec_b64 s[28:29], s[8:9]
	v_lshl_add_u32 v2, s0, 2, v47
	ds_write_b32 v2, v56 offset:49152
	s_or_b64 exec, exec, s[28:29]
	s_lshl_b32 s0, s0, 2
	s_add_i32 s0, s0, 0
	v_mov_b32_e32 v2, s0
	s_waitcnt lgkmcnt(0)
	s_barrier
	v_cmp_ne_u32_e32 vcc, 0, v56
	s_cbranch_vccz .LBB0_1010
	ds_read_b128 v[58:61], v2 offset:49152
	ds_read_b128 v[62:65], v2 offset:49168
	s_waitcnt lgkmcnt(1)
	v_and_b32_e32 v2, v59, v58
	v_and_b32_e32 v2, v2, v60
	v_and_b32_e32 v2, v2, v61
	s_waitcnt lgkmcnt(0)
	v_and_b32_e32 v2, v2, v62
	v_and_b32_e32 v2, v2, v63
	v_and_b32_e32 v2, v2, v64
	v_and_b32_e32 v2, v2, v65
	v_cmp_ne_u32_e32 vcc, 0, v2
	s_cbranch_vccz .LBB0_1010
